# HGRN chunk-top waits counted so the four younger y-stores stay in flight (waitcnt placement)
# speedup vs baseline: 1.0017x; 1.0017x over previous
; __device__ __forceinline__ int tid_() { int x = threadIdx.x; asm volatile("" : "+v"(x)); return x; }
; __device__ void mx_hgrn(const Params& P, int l, int item, char* lds) {
;     const int tid = tid_(), wid = tid >> 6, lane = tid & 63, fr = lane & 15, fq = lane >> 4;
;     const int b = item >> 4, h = (item >> 2) & 3, half = (item >> 1) & 1, dsel = item & 1;
;     const bf16_t* pr = (const bf16_t*)(P.ws + OFF_PREST) + (size_t)b * SQ * PREST_LD + HG_O;
;     bf16_t* YD = (bf16_t*)(P.ws + (dsel ? OFF_YD : OFF_Y0)) + (size_t)b * SQ * 512 + h * 128 + half * 64;
;     bf16_t* QT = (bf16_t*)lds; bf16_t* KT = QT + 64 * 136; bf16_t* ATT = KT + 128 * 72; bf16_t* VT = ATT + 64 * 72; bf16_t* ST = VT + 64 * 72;
;     float* TOT = (float*)(ST + 64 * 136);
;     const int dk = tid & 127, hf = tid >> 7;
;     const int i = wid * 16 + fr;
; #pragma unroll 1
;     for (int d = dsel; d <= dsel; ++d) {
;         const float lbv = ((const float*)(P.ws + OFF_LB))[(l * 2 + d) * 512 + h * 128 + dk], oml = 1.f - lbv;
;         f32x4 Sacc[2][4];
; #pragma unroll
;         for (int a = 0; a < 2; ++a)
; #pragma unroll
;             for (int dt = 0; dt < 4; ++dt) Sacc[a][dt] = (f32x4){0.f, 0.f, 0.f, 0.f};
;         __syncthreads();
;         for (int e = tid; e < 64 * 136 / 2; e += NT) ((unsigned*)ST)[e] = 0u;
;         __syncthreads();
;         u32x4 pff[4], pfq[4], pfv[2];
;         auto hg_load = [&](int cc) {
;             const int t0 = d ? SQ - 64 * (cc + 1) : 64 * cc;
; #pragma unroll
;             for (int it = 0; it < 4; ++it) {
;                 const int vi = tid + 256 * it, ii = vi >> 4, e = vi & 15, t = TROW(ii);
;                 pff[it] = *(const u32x4*)(pr + (size_t)t * PREST_LD + 512 * (1 + d) + h * 128 + e * 8);
;                 pfq[it] = *(const u32x4*)(pr + (size_t)t * PREST_LD + h * 128 + e * 8);
;             }
; #pragma unroll
;             for (int it = 0; it < 2; ++it) {
;                 const int vi = tid + 256 * it, ii = vi >> 3, e = vi & 7, t = TROW(ii);
;                 pfv[it] = *(const u32x4*)(pr + (size_t)t * PREST_LD + 1536 + h * 128 + half * 64 + e * 8);
;             }
;         };
;         hg_load(0);
.LBB0_515:
	s_or_b64 exec, exec, s[0:1]
	s_ashr_i32 s28, s30, 4
	s_ashr_i32 s29, s28, 31
	s_mul_i32 s1, s28, 0x1480000
	s_mul_hi_i32 s0, s28, 0x1480000
	s_add_u32 s1, s74, s1
	s_addc_u32 s26, s75, s0
	s_add_u32 s0, s1, 0xa001500
	s_addc_u32 s1, s26, 0
	s_cmp_eq_u32 s24, 0
	s_cselect_b64 vcc, -1, 0
	s_and_b64 s[40:41], vcc, exec
	s_mov_b32 s24, 0x22800000
	s_cselect_b32 s24, 0x24800000, s24
	s_add_u32 s24, s74, s24
	s_addc_u32 s26, s75, 0
	s_lshl_b64 s[28:29], s[28:29], 21
	s_add_u32 s27, s24, s28
	s_addc_u32 s26, s26, s29
	s_lshl_b32 s24, s21, 1
	s_add_u32 s27, s27, s24
	s_addc_u32 s26, s26, 0
	s_and_b32 s28, s38, 64
	s_lshl_b32 s28, s28, 1
	s_add_u32 s40, s27, s28
	s_addc_u32 s41, s26, 0
	s_waitcnt vmcnt(13)
	v_ashrrev_i32_e32 v7, 7, v42
	s_movk_i32 s26, 0x2200
	v_lshlrev_b32_e32 v0, 3, v42
	v_ashrrev_i32_e32 v43, 6, v42
	v_and_b32_e32 v45, 15, v42
	v_mul_lo_u32 v49, v7, s26
	s_movk_i32 s26, 0x80
	s_waitcnt vmcnt(6)
	v_and_b32_e32 v34, 56, v0
	v_lshl_or_b32 v126, v43, 4, v45
	v_add_u32_e32 v8, 0x200, v42
	v_readlane_b32 s27, v238, 9
	v_cmp_gt_u32_e64 s[38:39], s26, v42
	s_movk_i32 s26, 0x110
	v_mul_u32_u24_e32 v4, 0x90, v34
	v_mul_u32_u24_e32 v3, 0x90, v2
	v_bfe_u32 v5, v42, 4, 2
	v_ashrrev_i32_e32 v125, 4, v42
	v_and_b32_e32 v44, 0x78, v0
	v_add_u32_e32 v0, 0x100, v42
	v_ashrrev_i32_e32 v128, 4, v8
	v_add_u32_e32 v8, 0x300, v42
	v_lshlrev_b32_e32 v48, 1, v2
	v_lshl_add_u32 v134, v2, 2, s27
	v_mul_lo_u32 v2, v126, s26
	v_sub_u32_e32 v6, 0x7ff, v125
	v_ashrrev_i32_e32 v127, 4, v0
	v_ashrrev_i32_e32 v129, 4, v8
	v_add_u32_e32 v47, 0, v4
	v_add_u32_e32 v2, 0, v2
	v_lshlrev_b32_e32 v74, 3, v5
	v_lshlrev_b32_e32 v4, 4, v5
	v_lshlrev_b32_e32 v50, 2, v5
	v_lshlrev_b32_e32 v5, 7, v126
	v_cndmask_b32_e32 v6, v6, v125, vcc
	v_add_u32_e32 v135, v2, v4
	v_sub_u32_e32 v2, v2, v5
	v_mov_b32_e32 v75, v1
	v_mov_b64_e32 v[36:37], s[0:1]
	v_sub_u32_e32 v10, 0x7ff, v127
	v_sub_u32_e32 v18, 0x7ff, v128
	v_sub_u32_e32 v26, 0x7ff, v129
	v_add_u32_e32 v137, v2, v74
	v_add_u32_e32 v51, 0, v3
	v_lshl_add_u64 v[76:77], s[40:41], 0, v[74:75]
	v_mad_i64_i32 v[2:3], s[40:41], v6, s3, v[36:37]
	v_cndmask_b32_e32 v10, v10, v127, vcc
	v_cndmask_b32_e32 v18, v18, v128, vcc
	v_cndmask_b32_e32 v26, v26, v129, vcc
	s_lshl_b32 s40, s35, 1
	s_mov_b32 s41, s25
	v_mad_i64_i32 v[10:11], s[42:43], v10, s3, v[36:37]
	v_mad_i64_i32 v[18:19], s[42:43], v18, s3, v[36:37]
	v_mad_i64_i32 v[26:27], s[42:43], v26, s3, v[36:37]
	v_add_u32_e32 v136, 0, v4
	v_add_u32_e32 v53, s27, v4
	v_lshl_add_u64 v[4:5], v[2:3], 0, s[40:41]
	v_lshl_add_u64 v[12:13], v[10:11], 0, s[40:41]
	v_lshl_add_u64 v[20:21], v[18:19], 0, s[40:41]
	v_lshl_add_u64 v[28:29], v[26:27], 0, s[40:41]
	v_and_b32_e32 v130, 63, v178
	v_and_b32_e32 v131, 63, v178
	v_lshlrev_b32_e32 v0, 1, v44
	v_lshl_add_u64 v[4:5], v[4:5], 0, s[24:25]
	v_lshl_add_u64 v[2:3], v[2:3], 0, s[24:25]
	v_lshl_add_u64 v[12:13], v[12:13], 0, s[24:25]
	v_lshl_add_u64 v[10:11], v[10:11], 0, s[24:25]
	v_lshl_add_u64 v[20:21], v[20:21], 0, s[24:25]
	v_lshl_add_u64 v[18:19], v[18:19], 0, s[24:25]
	v_lshl_add_u64 v[28:29], v[28:29], 0, s[24:25]
	v_lshl_add_u64 v[26:27], v[26:27], 0, s[24:25]
	v_add_u32_e32 v46, 0, v0
	v_lshlrev_b32_e32 v52, 6, v7
	v_lshl_add_u64 v[4:5], v[4:5], 0, v[0:1]
	v_lshl_add_u64 v[6:7], v[2:3], 0, v[0:1]
	v_lshl_add_u64 v[12:13], v[12:13], 0, v[0:1]
	v_lshl_add_u64 v[14:15], v[10:11], 0, v[0:1]
	v_lshl_add_u64 v[20:21], v[20:21], 0, v[0:1]
	v_lshl_add_u64 v[22:23], v[18:19], 0, v[0:1]
	v_lshl_add_u64 v[28:29], v[28:29], 0, v[0:1]
	v_lshl_add_u64 v[30:31], v[26:27], 0, v[0:1]
	v_sub_u32_e32 v0, 0x7ff, v130
	v_cndmask_b32_e32 v0, v0, v130, vcc
	s_waitcnt vmcnt(5)
	v_mad_i64_i32 v[38:39], s[40:41], v0, s3, v[36:37]
	s_mov_b32 s29, s25
	v_lshl_add_u64 v[38:39], v[38:39], 0, s[24:25]
	v_sub_u32_e32 v40, 0x7ff, v131
	v_lshl_add_u64 v[38:39], v[38:39], 0, s[28:29]
	v_lshrrev_b32_e32 v0, 6, v178
	v_lshlrev_b32_e32 v0, 4, v0
	v_lshl_add_u64 v[34:35], v[38:39], 0, v[0:1]
	v_cndmask_b32_e32 v38, v40, v131, vcc
	v_mad_i64_i32 v[36:37], s[40:41], v38, s3, v[36:37]
	v_lshl_add_u64 v[36:37], v[36:37], 0, s[24:25]
	v_lshl_add_u64 v[36:37], v[36:37], 0, s[28:29]
	v_lshl_add_u64 v[38:39], v[36:37], 0, v[0:1]
	s_waitcnt lgkmcnt(0)
	s_barrier
	global_load_dwordx4 v[2:5], v[4:5], off offset:1024
	s_nop 0
	global_load_dwordx4 v[6:9], v[6:7], off
	s_nop 0
	global_load_dwordx4 v[10:13], v[12:13], off offset:1024
	s_nop 0
	global_load_dwordx4 v[14:17], v[14:15], off
	s_nop 0
	global_load_dwordx4 v[18:21], v[20:21], off offset:1024
	s_nop 0
	global_load_dwordx4 v[22:25], v[22:23], off
	s_nop 0
	global_load_dwordx4 v[26:29], v[28:29], off offset:1024
	s_nop 0
	global_load_dwordx4 v[30:33], v[30:31], off
	s_nop 0
	global_load_dwordx4 v[34:37], v[34:35], off offset:3072
	s_nop 0
	global_load_dwordx4 v[38:41], v[38:39], off offset:3136
	v_mad_u64_u32 v[78:79], s[40:41], v125, s26, v[46:47]
	v_mad_u64_u32 v[80:81], s[40:41], v127, s26, v[46:47]
	v_mad_u64_u32 v[82:83], s[40:41], v128, s26, v[46:47]
	v_mad_u64_u32 v[84:85], s[40:41], v129, s26, v[46:47]
	v_or_b32_e32 v46, 2, v50
	v_cmp_gt_i32_e64 s[44:45], v46, v126
	v_or_b32_e32 v46, 3, v50
	v_cmp_gt_i32_e64 s[46:47], v46, v126
	v_or_b32_e32 v46, 16, v50
	v_cmp_gt_i32_e64 s[48:49], v46, v126
	v_or_b32_e32 v46, 17, v50
	v_cmp_gt_i32_e64 s[50:51], v46, v126
	v_or_b32_e32 v46, 18, v50
	v_cmp_gt_i32_e64 s[52:53], v46, v126
	v_or_b32_e32 v46, 19, v50
	v_cmp_gt_i32_e64 s[54:55], v46, v126
	v_or_b32_e32 v46, 32, v50
	v_cmp_gt_i32_e64 s[56:57], v46, v126
	v_or_b32_e32 v46, 33, v50
	v_cmp_gt_i32_e64 s[58:59], v46, v126
	v_or_b32_e32 v46, 34, v50
	v_cmp_gt_i32_e64 s[60:61], v46, v126
	v_or_b32_e32 v46, 35, v50
	v_cmp_gt_i32_e64 s[62:63], v46, v126
	v_or_b32_e32 v46, 48, v50
	v_cmp_gt_i32_e64 s[64:65], v46, v126
	v_or_b32_e32 v46, 49, v50
	s_add_u32 s24, s0, s24
	v_lshl_add_u32 v133, v42, 2, s27
	v_sub_u32_e32 v54, v136, v74
	v_mad_u32_u24 v85, v45, s26, v188
	v_cmp_gt_i32_e64 s[66:67], v46, v126
	v_or_b32_e32 v46, 50, v50
	v_and_b32_e32 v42, 0xffffffc0, v42
	s_addc_u32 s26, s1, 0
	v_cmp_gt_i32_e64 s[68:69], v46, v126
	v_or_b32_e32 v46, 51, v50
	v_add_u32_e32 v138, v54, v42
	v_lshl_or_b32 v42, v43, 1, 1
	s_add_u32 s28, s24, s28
	v_mul_u32_u24_e32 v83, 0x110, v45
	v_cmp_gt_i32_e64 s[40:41], v50, v126
	v_cmp_lt_i32_e64 s[42:43], v50, v126
	v_cmp_gt_i32_e64 s[70:71], v46, v126
	v_mul_u32_u24_e32 v46, 0x90, v45
	v_lshl_or_b32 v50, v43, 5, v45
	v_lshl_or_b32 v45, v42, 4, v45
	s_addc_u32 s29, s26, 0
	v_lshrrev_b32_e32 v79, 6, v178
	v_mul_u32_u24_e32 v79, 0x480, v79
	v_lshl_add_u32 v79, v130, 1, v79
	v_add_u32_e32 v81, 0x1200, v79
	v_lshlrev_b32_e32 v47, 7, v43
	v_mul_lo_u32 v50, v50, s84
	v_lshlrev_b32_e32 v43, 6, v42
	v_mul_lo_u32 v45, v45, s84
	v_lshl_add_u64 v[86:87], s[28:29], 0, v[0:1]
	v_or_b32_e32 v0, v49, v48
	v_readlane_b32 s24, v238, 5
	v_mov_b32_e32 v88, 0
	s_mov_b32 s34, 0
	v_add3_u32 v132, 0, v49, v48
	s_waitcnt vmcnt(10)
; __device__ void mx_hgrn(const Params& P, int l, int item, char* lds) {
;     ...
;         f32x4 Sacc[2][4];
; #pragma unroll
;         for (int a = 0; a < 2; ++a)
; #pragma unroll
;             for (int dt = 0; dt < 4; ++dt) Sacc[a][dt] = (f32x4){0.f, 0.f, 0.f, 0.f};
;         __syncthreads();
;         for (int e = tid; e < 64 * 136 / 2; e += NT) ((unsigned*)ST)[e] = 0u;
;         __syncthreads();
;         u32x4 pff[4], pfq[4], pfv[2];
;         auto hg_load = [&](int cc) {
;             const int t0 = d ? SQ - 64 * (cc + 1) : 64 * cc;
; #pragma unroll
;             for (int it = 0; it < 4; ++it) {
;                 const int vi = tid + 256 * it, ii = vi >> 4, e = vi & 15, t = TROW(ii);
;                 pff[it] = *(const u32x4*)(pr + (size_t)t * PREST_LD + 512 * (1 + d) + h * 128 + e * 8);
;                 pfq[it] = *(const u32x4*)(pr + (size_t)t * PREST_LD + h * 128 + e * 8);
;             }
; #pragma unroll
;             for (int it = 0; it < 2; ++it) {
;                 const int vi = tid + 256 * it, ii = vi >> 3, e = vi & 7, t = TROW(ii);
;                 pfv[it] = *(const u32x4*)(pr + (size_t)t * PREST_LD + 1536 + h * 128 + half * 64 + e * 8);
;             }
;         };
;         hg_load(0);
; #pragma unroll 1
;         for (int c = 0; c < 32; ++c) {
;             const int t0 = d ? SQ - 64 * (c + 1) : 64 * c;
; #pragma unroll
;             for (int it = 0; it < 4; ++it) {
;                 const int vi = tid + 256 * it, ii = vi >> 4, e = vi & 15;
;                 *(u32x4*)(KT + ii * 136 + e * 8) = pff[it];
;                 *(u32x4*)(QT + ii * 136 + e * 8) = pfq[it];
;             }
; #pragma unroll
;             for (int it = 0; it < 2; ++it) {
;                 const int vi = tid + 256 * it, ii = vi >> 3, e = vi & 7;
;                 const u32x4 vv = pfv[it];
;                 VT[(e * 8 + 0) * 72 + ii] = (bf16_t)(vv.x & 0xffff); VT[(e * 8 + 1) * 72 + ii] = (bf16_t)(vv.x >> 16);
;                 VT[(e * 8 + 2) * 72 + ii] = (bf16_t)(vv.y & 0xffff); VT[(e * 8 + 3) * 72 + ii] = (bf16_t)(vv.y >> 16);
;                 VT[(e * 8 + 4) * 72 + ii] = (bf16_t)(vv.z & 0xffff); VT[(e * 8 + 5) * 72 + ii] = (bf16_t)(vv.z >> 16);
;                 VT[(e * 8 + 6) * 72 + ii] = (bf16_t)(vv.w & 0xffff); VT[(e * 8 + 7) * 72 + ii] = (bf16_t)(vv.w >> 16);
;             }
;             if (c + 1 < 32) hg_load(c + 1);
	v_sub_f32_e32 v75, 1.0, v124
	v_lshl_add_u32 v139, v42, 5, v54
	v_add_u32_e32 v140, s24, v0
	s_lshl_b32 s24, s35, 1
	s_lshl_b32 s72, s21, 1
	v_lshlrev_b32_e32 v0, 1, v44
	v_add_u32_e32 v141, v51, v52
	v_add_u32_e32 v142, v136, v46
	v_add_u32_e32 v143, v53, v47
	v_add_u32_e32 v144, v136, v50
	v_add_u32_e32 v145, v53, v43
	v_add_u32_e32 v146, v136, v45
	v_mov_b32_e32 v89, v88
	v_mov_b32_e32 v90, v88
	v_mov_b32_e32 v91, v88
	v_mov_b32_e32 v92, v88
	v_mov_b32_e32 v93, v88
	v_mov_b32_e32 v94, v88
	v_mov_b32_e32 v95, v88
	v_mov_b32_e32 v100, v88
	v_mov_b32_e32 v101, v88
	v_mov_b32_e32 v102, v88
	v_mov_b32_e32 v103, v88
	v_mov_b32_e32 v108, v88
	v_mov_b32_e32 v109, v88
	v_mov_b32_e32 v110, v88
	v_mov_b32_e32 v111, v88
	v_mov_b32_e32 v96, v88
	v_mov_b32_e32 v97, v88
	v_mov_b32_e32 v98, v88
	v_mov_b32_e32 v99, v88
	v_mov_b32_e32 v104, v88
	v_mov_b32_e32 v105, v88
	v_mov_b32_e32 v106, v88
	v_mov_b32_e32 v107, v88
	v_mov_b32_e32 v112, v88
	v_mov_b32_e32 v113, v88
	v_mov_b32_e32 v114, v88
	v_mov_b32_e32 v115, v88
	v_mov_b32_e32 v116, v88
	v_mov_b32_e32 v117, v88
	v_mov_b32_e32 v118, v88
	v_mov_b32_e32 v119, v88
	s_waitcnt vmcnt(0)
.LBB0_516:
	s_add_i32 s21, s34, 1
	s_cmp_eq_u32 s34, 31
	s_waitcnt vmcnt(13)
	ds_write_b128 v78, v[2:5] offset:17408
	s_waitcnt vmcnt(12)
	ds_write_b128 v78, v[6:9]
	s_waitcnt vmcnt(11)
	ds_write_b128 v80, v[10:13] offset:17408
	s_waitcnt vmcnt(10)
	ds_write_b128 v80, v[14:17]
	s_waitcnt vmcnt(9)
	ds_write_b128 v82, v[18:21] offset:17408
	s_waitcnt vmcnt(8)
	ds_write_b128 v82, v[22:25]
	s_waitcnt vmcnt(7)
	ds_write_b128 v84, v[26:29] offset:17408
	s_waitcnt vmcnt(6)
	ds_write_b128 v84, v[30:33]
	s_waitcnt vmcnt(5)
	ds_write_b16 v79, v34 offset:45056
	ds_write_b16_d16_hi v79, v34 offset:45200
	ds_write_b16 v79, v35 offset:45344
	ds_write_b16_d16_hi v79, v35 offset:45488
	ds_write_b16 v79, v36 offset:45632
	ds_write_b16_d16_hi v79, v36 offset:45776
	ds_write_b16 v79, v37 offset:45920
	ds_write_b16_d16_hi v79, v37 offset:46064
	s_waitcnt vmcnt(4)
	ds_write_b16 v81, v38 offset:45056
	ds_write_b16_d16_hi v81, v38 offset:45200
	ds_write_b16 v81, v39 offset:45344
	ds_write_b16_d16_hi v81, v39 offset:45488
	ds_write_b16 v81, v40 offset:45632
	ds_write_b16_d16_hi v81, v40 offset:45776
	ds_write_b16 v81, v41 offset:45920
	ds_write_b16_d16_hi v81, v41 offset:46064
	s_cbranch_scc1 .LBB0_518
	s_lshl_b32 s26, s21, 6
	s_sub_i32 s27, 0x7c0, s26
	s_and_b64 s[28:29], vcc, exec
	s_cselect_b32 s27, s26, s27
	s_or_b32 s27, s27, 63
	v_sub_u32_e32 v2, s27, v125
	v_add_u32_e32 v3, s26, v125
	v_sub_u32_e32 v10, s27, v127
	v_add_u32_e32 v11, s26, v127
	v_sub_u32_e32 v18, s27, v128
	v_add_u32_e32 v19, s26, v128
	v_sub_u32_e32 v28, s27, v129
	v_add_u32_e32 v29, s26, v129
	v_cndmask_b32_e32 v2, v2, v3, vcc
	v_mov_b64_e32 v[26:27], s[0:1]
	v_cndmask_b32_e32 v10, v10, v11, vcc
	v_cndmask_b32_e32 v18, v18, v19, vcc
	v_cndmask_b32_e32 v28, v28, v29, vcc
	v_mad_i64_i32 v[2:3], s[28:29], v2, s3, v[26:27]
	v_mad_i64_i32 v[10:11], s[28:29], v10, s3, v[26:27]
	v_mad_i64_i32 v[18:19], s[28:29], v18, s3, v[26:27]
	v_mad_i64_i32 v[26:27], s[28:29], v28, s3, v[26:27]
	v_lshl_add_u64 v[4:5], v[2:3], 0, s[24:25]
	s_mov_b32 s73, s25
	v_lshl_add_u64 v[12:13], v[10:11], 0, s[24:25]
	v_lshl_add_u64 v[20:21], v[18:19], 0, s[24:25]
	v_lshl_add_u64 v[28:29], v[26:27], 0, s[24:25]
	v_sub_u32_e32 v34, s27, v130
	v_add_u32_e32 v35, s26, v130
	v_sub_u32_e32 v36, s27, v131
	v_add_u32_e32 v37, s26, v131
	v_lshl_add_u64 v[4:5], v[4:5], 0, s[72:73]
	v_lshl_add_u64 v[2:3], v[2:3], 0, s[72:73]
	v_lshl_add_u64 v[12:13], v[12:13], 0, s[72:73]
	v_lshl_add_u64 v[10:11], v[10:11], 0, s[72:73]
	v_lshl_add_u64 v[20:21], v[20:21], 0, s[72:73]
	v_lshl_add_u64 v[18:19], v[18:19], 0, s[72:73]
	v_lshl_add_u64 v[28:29], v[28:29], 0, s[72:73]
	v_lshl_add_u64 v[26:27], v[26:27], 0, s[72:73]
	v_cndmask_b32_e32 v34, v34, v35, vcc
	v_cndmask_b32_e32 v36, v36, v37, vcc
	v_lshl_add_u64 v[4:5], v[4:5], 0, v[0:1]
	v_lshl_add_u64 v[6:7], v[2:3], 0, v[0:1]
	v_lshl_add_u64 v[12:13], v[12:13], 0, v[0:1]
	v_lshl_add_u64 v[14:15], v[10:11], 0, v[0:1]
	v_lshl_add_u64 v[20:21], v[20:21], 0, v[0:1]
	v_lshl_add_u64 v[22:23], v[18:19], 0, v[0:1]
	v_lshl_add_u64 v[28:29], v[28:29], 0, v[0:1]
	v_lshl_add_u64 v[30:31], v[26:27], 0, v[0:1]
	v_mad_i64_i32 v[34:35], s[28:29], v34, s3, v[86:87]
	v_mad_i64_i32 v[38:39], s[28:29], v36, s3, v[86:87]
	global_load_dwordx4 v[2:5], v[4:5], off offset:1024
	s_nop 0
	global_load_dwordx4 v[6:9], v[6:7], off
	s_nop 0
	global_load_dwordx4 v[10:13], v[12:13], off offset:1024
	s_nop 0
	global_load_dwordx4 v[14:17], v[14:15], off
	s_nop 0
	global_load_dwordx4 v[18:21], v[20:21], off offset:1024
	s_nop 0
	global_load_dwordx4 v[22:25], v[22:23], off
	s_nop 0
	global_load_dwordx4 v[26:29], v[28:29], off offset:1024
	s_nop 0
	global_load_dwordx4 v[30:33], v[30:31], off
	s_nop 0
	global_load_dwordx4 v[34:37], v[34:35], off offset:3072
	s_nop 0
	global_load_dwordx4 v[38:41], v[38:39], off offset:3136
